# v31 + window-cache output copy moved from phase 0 to the idle workgroups of layer-1 up-projection round 9
# speedup vs baseline: 1.0100x; 1.0039x over previous
.LBB0_165:
	s_ashr_i32 s39, s38, 31
	s_mov_b64 s[4:5], exec

.LBB0_1926:
	s_andn2_b64 vcc, exec, s[82:83]
	s_cbranch_vccz .LBB0_1915
	global_store_dword v161, v229, s[42:43] sc1
	s_branch .LBB0_1915
.Lrelay_1145:
	s_branch .LBB0_1145

.Lrelay_1143:
	s_branch .LBB0_1143
.LBB0_1928:
	s_and_b64 vcc, exec, s[6:7]
	s_cbranch_vccz .LBB0_1930
	s_barrier

.Lwd_entry:
	s_cmpk_lt_u32 s101, 32
	s_cbranch_scc1 .Lcv2_skip
	v_writelane_b32 v200, s2, 0
	v_writelane_b32 v200, s3, 1
	v_writelane_b32 v200, s4, 2
	v_writelane_b32 v200, s5, 3
	v_writelane_b32 v200, s6, 4
	v_writelane_b32 v200, s7, 5
	v_writelane_b32 v200, s8, 6
	v_writelane_b32 v200, s9, 7
	v_writelane_b32 v200, s10, 8
	v_writelane_b32 v200, s11, 9
	v_writelane_b32 v200, s12, 10
	v_writelane_b32 v200, s13, 11
	v_writelane_b32 v200, s14, 12
	v_writelane_b32 v200, s15, 13
	s_load_dwordx2 s[10:11], s[0:1], 0x18
	s_load_dwordx2 s[6:7], s[0:1], 0xb8
	v_mbcnt_lo_u32_b32 v0, -1, 0
	v_mbcnt_hi_u32_b32 v0, -1, v0
	v_readlane_b32 s4, v255, 4
	s_nop 1
	v_lshl_add_u32 v0, s4, 6, v0
	s_sub_i32 s4, s101, 32
	s_lshl_b32 s4, s4, 9
	v_or_b32_e32 v2, s4, v0
	s_mov_b32 s8, 0x1c000
	s_mov_b32 s3, 0x2040811
	s_mov_b32 s12, 0x1fbfff
	s_waitcnt lgkmcnt(0)
	s_add_u32 s6, s6, 0x8500000
	s_addc_u32 s7, s7, 0
	s_add_u32 s10, s10, 0x2000
	s_addc_u32 s11, s11, 0
	v_min_u32_e32 v4, s12, v2
	v_add_u32_e32 v2, s8, v2
	v_min_u32_e32 v5, s12, v2
	v_add_u32_e32 v2, s8, v2
	v_min_u32_e32 v6, s12, v2
	v_add_u32_e32 v2, s8, v2
	v_min_u32_e32 v7, s12, v2
	v_add_u32_e32 v2, s8, v2
	v_min_u32_e32 v8, s12, v2
	v_add_u32_e32 v2, s8, v2
	v_min_u32_e32 v9, s12, v2
	v_add_u32_e32 v2, s8, v2
	v_min_u32_e32 v10, s12, v2
	v_add_u32_e32 v2, s8, v2
	v_min_u32_e32 v11, s12, v2
	v_add_u32_e32 v2, s8, v2
	v_lshrrev_b32_e32 v12, 9, v4
	v_mul_hi_u32 v12, v12, s3
	v_mul_u32_u24_e32 v13, 0xfe00, v12
	v_sub_u32_e32 v13, v4, v13
	v_lshlrev_b32_e32 v12, 20, v12
	v_lshl_add_u32 v4, v13, 4, v12
	global_load_dwordx4 v[32:35], v4, s[10:11]
	v_lshrrev_b32_e32 v12, 9, v5
	v_mul_hi_u32 v12, v12, s3
	v_mul_u32_u24_e32 v13, 0xfe00, v12
	v_sub_u32_e32 v13, v5, v13
	v_lshlrev_b32_e32 v12, 20, v12
	v_lshl_add_u32 v5, v13, 4, v12
	global_load_dwordx4 v[36:39], v5, s[10:11]
	v_lshrrev_b32_e32 v12, 9, v6
	v_mul_hi_u32 v12, v12, s3
	v_mul_u32_u24_e32 v13, 0xfe00, v12
	v_sub_u32_e32 v13, v6, v13
	v_lshlrev_b32_e32 v12, 20, v12
	v_lshl_add_u32 v6, v13, 4, v12
	global_load_dwordx4 v[40:43], v6, s[10:11]
	v_lshrrev_b32_e32 v12, 9, v7
	v_mul_hi_u32 v12, v12, s3
	v_mul_u32_u24_e32 v13, 0xfe00, v12
	v_sub_u32_e32 v13, v7, v13
	v_lshlrev_b32_e32 v12, 20, v12
	v_lshl_add_u32 v7, v13, 4, v12
	global_load_dwordx4 v[44:47], v7, s[10:11]
	v_lshrrev_b32_e32 v12, 9, v8
	v_mul_hi_u32 v12, v12, s3
	v_mul_u32_u24_e32 v13, 0xfe00, v12
	v_sub_u32_e32 v13, v8, v13
	v_lshlrev_b32_e32 v12, 20, v12
	v_lshl_add_u32 v8, v13, 4, v12
	global_load_dwordx4 v[48:51], v8, s[10:11]
	v_lshrrev_b32_e32 v12, 9, v9
	v_mul_hi_u32 v12, v12, s3
	v_mul_u32_u24_e32 v13, 0xfe00, v12
	v_sub_u32_e32 v13, v9, v13
	v_lshlrev_b32_e32 v12, 20, v12
	v_lshl_add_u32 v9, v13, 4, v12
	global_load_dwordx4 v[52:55], v9, s[10:11]
	v_lshrrev_b32_e32 v12, 9, v10
	v_mul_hi_u32 v12, v12, s3
	v_mul_u32_u24_e32 v13, 0xfe00, v12
	v_sub_u32_e32 v13, v10, v13
	v_lshlrev_b32_e32 v12, 20, v12
	v_lshl_add_u32 v10, v13, 4, v12
	global_load_dwordx4 v[56:59], v10, s[10:11]
	v_lshrrev_b32_e32 v12, 9, v11
	v_mul_hi_u32 v12, v12, s3
	v_mul_u32_u24_e32 v13, 0xfe00, v12
	v_sub_u32_e32 v13, v11, v13
	v_lshlrev_b32_e32 v12, 20, v12
	v_lshl_add_u32 v11, v13, 4, v12
	global_load_dwordx4 v[60:63], v11, s[10:11]
	s_waitcnt vmcnt(0)
	global_store_dwordx4 v4, v[32:35], s[6:7]
	global_store_dwordx4 v5, v[36:39], s[6:7]
	global_store_dwordx4 v6, v[40:43], s[6:7]
	global_store_dwordx4 v7, v[44:47], s[6:7]
	global_store_dwordx4 v8, v[48:51], s[6:7]
	global_store_dwordx4 v9, v[52:55], s[6:7]
	global_store_dwordx4 v10, v[56:59], s[6:7]
	global_store_dwordx4 v11, v[60:63], s[6:7]
	s_nop 1
	v_min_u32_e32 v4, s12, v2
	v_add_u32_e32 v2, s8, v2
	v_min_u32_e32 v5, s12, v2
	v_add_u32_e32 v2, s8, v2
	v_min_u32_e32 v6, s12, v2
	v_add_u32_e32 v2, s8, v2
	v_min_u32_e32 v7, s12, v2
	v_add_u32_e32 v2, s8, v2
	v_min_u32_e32 v8, s12, v2
	v_add_u32_e32 v2, s8, v2
	v_min_u32_e32 v9, s12, v2
	v_add_u32_e32 v2, s8, v2
	v_min_u32_e32 v10, s12, v2
	v_add_u32_e32 v2, s8, v2
	v_min_u32_e32 v11, s12, v2
	v_add_u32_e32 v2, s8, v2
	v_lshrrev_b32_e32 v12, 9, v4
	v_mul_hi_u32 v12, v12, s3
	v_mul_u32_u24_e32 v13, 0xfe00, v12
	v_sub_u32_e32 v13, v4, v13
	v_lshlrev_b32_e32 v12, 20, v12
	v_lshl_add_u32 v4, v13, 4, v12
	global_load_dwordx4 v[32:35], v4, s[10:11]
	v_lshrrev_b32_e32 v12, 9, v5
	v_mul_hi_u32 v12, v12, s3
	v_mul_u32_u24_e32 v13, 0xfe00, v12
	v_sub_u32_e32 v13, v5, v13
	v_lshlrev_b32_e32 v12, 20, v12
	v_lshl_add_u32 v5, v13, 4, v12
	global_load_dwordx4 v[36:39], v5, s[10:11]
	v_lshrrev_b32_e32 v12, 9, v6
	v_mul_hi_u32 v12, v12, s3
	v_mul_u32_u24_e32 v13, 0xfe00, v12
	v_sub_u32_e32 v13, v6, v13
	v_lshlrev_b32_e32 v12, 20, v12
	v_lshl_add_u32 v6, v13, 4, v12
	global_load_dwordx4 v[40:43], v6, s[10:11]
	v_lshrrev_b32_e32 v12, 9, v7
	v_mul_hi_u32 v12, v12, s3
	v_mul_u32_u24_e32 v13, 0xfe00, v12
	v_sub_u32_e32 v13, v7, v13
	v_lshlrev_b32_e32 v12, 20, v12
	v_lshl_add_u32 v7, v13, 4, v12
	global_load_dwordx4 v[44:47], v7, s[10:11]
	v_lshrrev_b32_e32 v12, 9, v8
	v_mul_hi_u32 v12, v12, s3
	v_mul_u32_u24_e32 v13, 0xfe00, v12
	v_sub_u32_e32 v13, v8, v13
	v_lshlrev_b32_e32 v12, 20, v12
	v_lshl_add_u32 v8, v13, 4, v12
	global_load_dwordx4 v[48:51], v8, s[10:11]
	v_lshrrev_b32_e32 v12, 9, v9
	v_mul_hi_u32 v12, v12, s3
	v_mul_u32_u24_e32 v13, 0xfe00, v12
	v_sub_u32_e32 v13, v9, v13
	v_lshlrev_b32_e32 v12, 20, v12
	v_lshl_add_u32 v9, v13, 4, v12
	global_load_dwordx4 v[52:55], v9, s[10:11]
	v_lshrrev_b32_e32 v12, 9, v10
	v_mul_hi_u32 v12, v12, s3
	v_mul_u32_u24_e32 v13, 0xfe00, v12
	v_sub_u32_e32 v13, v10, v13
	v_lshlrev_b32_e32 v12, 20, v12
	v_lshl_add_u32 v10, v13, 4, v12
	global_load_dwordx4 v[56:59], v10, s[10:11]
	v_lshrrev_b32_e32 v12, 9, v11
	v_mul_hi_u32 v12, v12, s3
	v_mul_u32_u24_e32 v13, 0xfe00, v12
	v_sub_u32_e32 v13, v11, v13
	v_lshlrev_b32_e32 v12, 20, v12
	v_lshl_add_u32 v11, v13, 4, v12
	global_load_dwordx4 v[60:63], v11, s[10:11]
	s_waitcnt vmcnt(0)
	global_store_dwordx4 v4, v[32:35], s[6:7]
	global_store_dwordx4 v5, v[36:39], s[6:7]
	global_store_dwordx4 v6, v[40:43], s[6:7]
	global_store_dwordx4 v7, v[44:47], s[6:7]
	global_store_dwordx4 v8, v[48:51], s[6:7]
	global_store_dwordx4 v9, v[52:55], s[6:7]
	global_store_dwordx4 v10, v[56:59], s[6:7]
	global_store_dwordx4 v11, v[60:63], s[6:7]
	s_nop 1
	v_min_u32_e32 v4, s12, v2
	v_add_u32_e32 v2, s8, v2
	v_min_u32_e32 v5, s12, v2
	v_add_u32_e32 v2, s8, v2
	v_min_u32_e32 v6, s12, v2
	v_add_u32_e32 v2, s8, v2
	v_lshrrev_b32_e32 v12, 9, v4
	v_mul_hi_u32 v12, v12, s3
	v_mul_u32_u24_e32 v13, 0xfe00, v12
	v_sub_u32_e32 v13, v4, v13
	v_lshlrev_b32_e32 v12, 20, v12
	v_lshl_add_u32 v4, v13, 4, v12
	global_load_dwordx4 v[32:35], v4, s[10:11]
	v_lshrrev_b32_e32 v12, 9, v5
	v_mul_hi_u32 v12, v12, s3
	v_mul_u32_u24_e32 v13, 0xfe00, v12
	v_sub_u32_e32 v13, v5, v13
	v_lshlrev_b32_e32 v12, 20, v12
	v_lshl_add_u32 v5, v13, 4, v12
	global_load_dwordx4 v[36:39], v5, s[10:11]
	v_lshrrev_b32_e32 v12, 9, v6
	v_mul_hi_u32 v12, v12, s3
	v_mul_u32_u24_e32 v13, 0xfe00, v12
	v_sub_u32_e32 v13, v6, v13
	v_lshlrev_b32_e32 v12, 20, v12
	v_lshl_add_u32 v6, v13, 4, v12
	global_load_dwordx4 v[40:43], v6, s[10:11]
	s_waitcnt vmcnt(0)
	global_store_dwordx4 v4, v[32:35], s[6:7]
	global_store_dwordx4 v5, v[36:39], s[6:7]
	global_store_dwordx4 v6, v[40:43], s[6:7]
	s_nop 1
	v_readlane_b32 s2, v200, 0
	v_readlane_b32 s3, v200, 1
	v_readlane_b32 s4, v200, 2
	v_readlane_b32 s5, v200, 3
	v_readlane_b32 s6, v200, 4
	v_readlane_b32 s7, v200, 5
	v_readlane_b32 s8, v200, 6
	v_readlane_b32 s9, v200, 7
	v_readlane_b32 s10, v200, 8
	v_readlane_b32 s11, v200, 9
	v_readlane_b32 s12, v200, 10
	v_readlane_b32 s13, v200, 11
	v_readlane_b32 s14, v200, 12
	v_readlane_b32 s15, v200, 13
	s_branch .Lcv2_skip
